# plus: accumulator clearing between tiles with v_pk_mov_b32 pairs
# baseline (speedup 1.0000x reference)
; template <class Epi, class Sched, bool ALIGN_EPI = false, bool SP2 = false>
; __device__ __forceinline__ void gemm_phase(PG8_LAS unsigned char* lds, const Gemm g, const Sched& S, const Epi& E, int wave_in) {
;     ...
;         const char* nA = has_next ? (const char*)g.A + (size_t)nxt.pm * tstepA : cA; const char* nB = has_next ? (const char*)g.Bt + (size_t)nxt.pn * tstep : cB;
;     ...
; #pragma unroll
;         for (int a = 0; a < 2; ++a)
; #pragma unroll
;             for (int b = 0; b < 2; ++b)
; #pragma unroll
;                 for (int m = 0; m < 4; ++m)
; #pragma unroll
;                     for (int n = 0; n < 2; ++n) acc[a][b][m][n] = (f32x4){0.f, 0.f, 0.f, 0.f};
;         cur = nxt; cA = nA; cB = nB; ++ui;
.LBB0_42:
	s_ashr_i32 s43, s42, 31
	s_lshl_b64 s[44:45], s[42:43], 20
	v_readlane_b32 s46, v253, 60
	v_readlane_b32 s47, v253, 61
	s_add_u32 s44, s46, s44
	s_addc_u32 s45, s47, s45
	s_and_b64 s[46:47], s[8:9], exec
	s_cselect_b32 s43, s45, s49
	s_cselect_b32 s67, s44, s48
	s_ashr_i32 s41, s40, 31
	s_lshl_b64 s[46:47], s[40:41], 20
	s_add_u32 s46, s54, s46
	s_addc_u32 s47, s55, s47
	s_and_b64 s[52:53], s[8:9], exec
	s_cselect_b32 s41, s47, s51
	s_cselect_b32 s68, s46, s50
	s_add_u32 s48, s48, 0x80080
	s_addc_u32 s49, s49, 0
	s_add_u32 s69, s50, 0x100
	v_mov_b32_e32 v2, 0
	s_addc_u32 s70, s51, 0
	s_mov_b32 s71, -2
	v_mov_b32_e32 v3, v2
	v_pk_mov_b32 v[4:5], v[2:3], v[2:3]
	v_pk_mov_b32 v[66:67], v[2:3], v[2:3]
	v_pk_mov_b32 v[68:69], v[2:3], v[2:3]
	v_pk_mov_b32 v[10:11], v[2:3], v[2:3]
	v_pk_mov_b32 v[12:13], v[2:3], v[2:3]
	v_pk_mov_b32 v[74:75], v[2:3], v[2:3]
	v_pk_mov_b32 v[76:77], v[2:3], v[2:3]
	v_pk_mov_b32 v[18:19], v[2:3], v[2:3]
	s_waitcnt vmcnt(0)
	v_pk_mov_b32 v[20:21], v[2:3], v[2:3]
	v_pk_mov_b32 v[82:83], v[2:3], v[2:3]
	v_pk_mov_b32 v[84:85], v[2:3], v[2:3]
	v_pk_mov_b32 v[26:27], v[2:3], v[2:3]
	v_pk_mov_b32 v[28:29], v[2:3], v[2:3]
	v_pk_mov_b32 v[90:91], v[2:3], v[2:3]
	v_pk_mov_b32 v[92:93], v[2:3], v[2:3]
	v_pk_mov_b32 v[6:7], v[2:3], v[2:3]
	v_pk_mov_b32 v[8:9], v[2:3], v[2:3]
	v_pk_mov_b32 v[70:71], v[2:3], v[2:3]
	v_pk_mov_b32 v[72:73], v[2:3], v[2:3]
	v_pk_mov_b32 v[14:15], v[2:3], v[2:3]
	v_pk_mov_b32 v[16:17], v[2:3], v[2:3]
	v_pk_mov_b32 v[78:79], v[2:3], v[2:3]
	v_pk_mov_b32 v[80:81], v[2:3], v[2:3]
	v_pk_mov_b32 v[22:23], v[2:3], v[2:3]
	v_pk_mov_b32 v[24:25], v[2:3], v[2:3]
	v_pk_mov_b32 v[86:87], v[2:3], v[2:3]
	v_pk_mov_b32 v[88:89], v[2:3], v[2:3]
	v_pk_mov_b32 v[30:31], v[2:3], v[2:3]
	v_pk_mov_b32 v[32:33], v[2:3], v[2:3]
	v_pk_mov_b32 v[94:95], v[2:3], v[2:3]
	v_pk_mov_b32 v[96:97], v[2:3], v[2:3]
	v_pk_mov_b32 v[34:35], v[2:3], v[2:3]
	v_pk_mov_b32 v[36:37], v[2:3], v[2:3]
	v_pk_mov_b32 v[98:99], v[2:3], v[2:3]
	v_pk_mov_b32 v[100:101], v[2:3], v[2:3]
	v_pk_mov_b32 v[42:43], v[2:3], v[2:3]
	v_pk_mov_b32 v[44:45], v[2:3], v[2:3]
	v_pk_mov_b32 v[138:139], v[2:3], v[2:3]
	v_pk_mov_b32 v[140:141], v[2:3], v[2:3]
	v_pk_mov_b32 v[50:51], v[2:3], v[2:3]
	v_pk_mov_b32 v[52:53], v[2:3], v[2:3]
	v_pk_mov_b32 v[146:147], v[2:3], v[2:3]
	v_pk_mov_b32 v[148:149], v[2:3], v[2:3]
	v_pk_mov_b32 v[58:59], v[2:3], v[2:3]
	v_pk_mov_b32 v[60:61], v[2:3], v[2:3]
	v_pk_mov_b32 v[134:135], v[2:3], v[2:3]
	v_pk_mov_b32 v[136:137], v[2:3], v[2:3]
	v_pk_mov_b32 v[38:39], v[2:3], v[2:3]
	v_pk_mov_b32 v[40:41], v[2:3], v[2:3]
	v_pk_mov_b32 v[102:103], v[2:3], v[2:3]
	v_pk_mov_b32 v[104:105], v[2:3], v[2:3]
	v_pk_mov_b32 v[46:47], v[2:3], v[2:3]
	v_pk_mov_b32 v[48:49], v[2:3], v[2:3]
	v_pk_mov_b32 v[142:143], v[2:3], v[2:3]
	v_pk_mov_b32 v[144:145], v[2:3], v[2:3]
	v_pk_mov_b32 v[54:55], v[2:3], v[2:3]
	v_pk_mov_b32 v[56:57], v[2:3], v[2:3]
	v_pk_mov_b32 v[150:151], v[2:3], v[2:3]
	v_pk_mov_b32 v[152:153], v[2:3], v[2:3]
	v_pk_mov_b32 v[62:63], v[2:3], v[2:3]
	v_pk_mov_b32 v[64:65], v[2:3], v[2:3]
	v_pk_mov_b32 v[154:155], v[2:3], v[2:3]
	v_pk_mov_b32 v[156:157], v[2:3], v[2:3]

; template <class Epi, class Sched, bool ALIGN_EPI = false, bool SP2 = false>
; __device__ __forceinline__ void gemm_phase(PG8_LAS unsigned char* lds, const Gemm g, const Sched& S, const Epi& E, int wave_in) {
;     ...
;         const char* nA = has_next ? (const char*)g.A + (size_t)nxt.pm * tstepA : cA; const char* nB = has_next ? (const char*)g.Bt + (size_t)nxt.pn * tstep : cB;
;     ...
; #pragma unroll
;         for (int a = 0; a < 2; ++a)
; #pragma unroll
;             for (int b = 0; b < 2; ++b)
; #pragma unroll
;                 for (int m = 0; m < 4; ++m)
; #pragma unroll
;                     for (int n = 0; n < 2; ++n) acc[a][b][m][n] = (f32x4){0.f, 0.f, 0.f, 0.f};
;         cur = nxt; cA = nA; cB = nB; ++ui;
.LBB0_83:
	s_ashr_i32 s17, s16, 31
	s_lshl_b64 s[18:19], s[16:17], 20
	v_readlane_b32 s20, v253, 62
	v_readlane_b32 s21, v253, 63
	s_add_u32 s18, s20, s18
	s_addc_u32 s19, s21, s19
	s_and_b64 s[20:21], s[4:5], exec
	s_cselect_b32 s17, s19, s23
	s_cselect_b32 s42, s18, s22
	s_ashr_i32 s11, s10, 31
	s_lshl_b64 s[20:21], s[10:11], 19
	s_add_u32 s20, s28, s20
	s_addc_u32 s21, s29, s21
	s_and_b64 s[26:27], s[4:5], exec
	s_cselect_b32 s11, s21, s25
	s_cselect_b32 s43, s20, s24
	s_add_u32 s22, s22, 0x80080
	s_addc_u32 s23, s23, 0
	s_add_u32 s44, s24, 0x100
	v_mov_b32_e32 v2, 0
	s_addc_u32 s45, s25, 0
	s_mov_b32 s46, -2
	v_mov_b32_e32 v3, v2
	v_pk_mov_b32 v[4:5], v[2:3], v[2:3]
	v_pk_mov_b32 v[6:7], v[2:3], v[2:3]
	v_pk_mov_b32 v[8:9], v[2:3], v[2:3]
	v_pk_mov_b32 v[14:15], v[2:3], v[2:3]
	v_pk_mov_b32 v[16:17], v[2:3], v[2:3]
	v_pk_mov_b32 v[18:19], v[2:3], v[2:3]
	s_waitcnt vmcnt(0)
	v_pk_mov_b32 v[20:21], v[2:3], v[2:3]
	v_pk_mov_b32 v[30:31], v[2:3], v[2:3]
	v_pk_mov_b32 v[32:33], v[2:3], v[2:3]
	v_pk_mov_b32 v[34:35], v[2:3], v[2:3]
	v_pk_mov_b32 v[36:37], v[2:3], v[2:3]
	v_pk_mov_b32 v[46:47], v[2:3], v[2:3]
	v_pk_mov_b32 v[48:49], v[2:3], v[2:3]
	v_pk_mov_b32 v[50:51], v[2:3], v[2:3]
	v_pk_mov_b32 v[52:53], v[2:3], v[2:3]
	v_pk_mov_b32 v[10:11], v[2:3], v[2:3]
	v_pk_mov_b32 v[12:13], v[2:3], v[2:3]
	v_pk_mov_b32 v[22:23], v[2:3], v[2:3]
	v_pk_mov_b32 v[24:25], v[2:3], v[2:3]
	v_pk_mov_b32 v[26:27], v[2:3], v[2:3]
	v_pk_mov_b32 v[28:29], v[2:3], v[2:3]
	v_pk_mov_b32 v[38:39], v[2:3], v[2:3]
	v_pk_mov_b32 v[40:41], v[2:3], v[2:3]
	v_pk_mov_b32 v[42:43], v[2:3], v[2:3]
	v_pk_mov_b32 v[44:45], v[2:3], v[2:3]
	v_pk_mov_b32 v[54:55], v[2:3], v[2:3]
	v_pk_mov_b32 v[56:57], v[2:3], v[2:3]
	v_pk_mov_b32 v[58:59], v[2:3], v[2:3]
	v_pk_mov_b32 v[60:61], v[2:3], v[2:3]
	v_pk_mov_b32 v[62:63], v[2:3], v[2:3]
	v_pk_mov_b32 v[64:65], v[2:3], v[2:3]
	v_pk_mov_b32 v[66:67], v[2:3], v[2:3]
	v_pk_mov_b32 v[68:69], v[2:3], v[2:3]
	v_pk_mov_b32 v[70:71], v[2:3], v[2:3]
	v_pk_mov_b32 v[72:73], v[2:3], v[2:3]
	v_pk_mov_b32 v[78:79], v[2:3], v[2:3]
	v_pk_mov_b32 v[80:81], v[2:3], v[2:3]
	v_pk_mov_b32 v[82:83], v[2:3], v[2:3]
	v_pk_mov_b32 v[84:85], v[2:3], v[2:3]
	v_pk_mov_b32 v[94:95], v[2:3], v[2:3]
	v_pk_mov_b32 v[96:97], v[2:3], v[2:3]
	v_pk_mov_b32 v[98:99], v[2:3], v[2:3]
	v_pk_mov_b32 v[100:101], v[2:3], v[2:3]
	v_pk_mov_b32 v[110:111], v[2:3], v[2:3]
	v_pk_mov_b32 v[112:113], v[2:3], v[2:3]
	v_pk_mov_b32 v[114:115], v[2:3], v[2:3]
	v_pk_mov_b32 v[116:117], v[2:3], v[2:3]
	v_pk_mov_b32 v[74:75], v[2:3], v[2:3]
	v_pk_mov_b32 v[76:77], v[2:3], v[2:3]
	v_pk_mov_b32 v[86:87], v[2:3], v[2:3]
	v_pk_mov_b32 v[88:89], v[2:3], v[2:3]
	v_pk_mov_b32 v[90:91], v[2:3], v[2:3]
	v_pk_mov_b32 v[92:93], v[2:3], v[2:3]
	v_pk_mov_b32 v[102:103], v[2:3], v[2:3]
	v_pk_mov_b32 v[104:105], v[2:3], v[2:3]
	v_pk_mov_b32 v[106:107], v[2:3], v[2:3]
	v_pk_mov_b32 v[108:109], v[2:3], v[2:3]
	v_pk_mov_b32 v[118:119], v[2:3], v[2:3]
	v_pk_mov_b32 v[120:121], v[2:3], v[2:3]
	v_pk_mov_b32 v[122:123], v[2:3], v[2:3]
	v_pk_mov_b32 v[124:125], v[2:3], v[2:3]
	v_pk_mov_b32 v[126:127], v[2:3], v[2:3]
	v_pk_mov_b32 v[128:129], v[2:3], v[2:3]

; template <class Epi, class Sched, bool ALIGN_EPI = false, bool SP2 = false>
; __device__ __forceinline__ void gemm_phase(PG8_LAS unsigned char* lds, const Gemm g, const Sched& S, const Epi& E, int wave_in) {
;     ...
;         const char* nA = has_next ? (const char*)g.A + (size_t)nxt.pm * tstepA : cA; const char* nB = has_next ? (const char*)g.Bt + (size_t)nxt.pn * tstep : cB;
;     ...
; #pragma unroll
;         for (int a = 0; a < 2; ++a)
; #pragma unroll
;             for (int b = 0; b < 2; ++b)
; #pragma unroll
;                 for (int m = 0; m < 4; ++m)
; #pragma unroll
;                     for (int n = 0; n < 2; ++n) acc[a][b][m][n] = (f32x4){0.f, 0.f, 0.f, 0.f};
;         cur = nxt; cA = nA; cB = nB; ++ui;
.LBB0_106:
	s_ashr_i32 s21, s20, 31
	s_lshl_b64 s[22:23], s[20:21], 20
	s_add_u32 s22, s36, s22
	s_addc_u32 s23, s37, s23
	s_and_b64 s[24:25], s[4:5], exec
	s_cselect_b32 s21, s23, s27
	s_cselect_b32 s50, s22, s26
	s_ashr_i32 s19, s18, 31
	s_lshl_b64 s[24:25], s[18:19], 18
	s_add_u32 s24, s38, s24
	s_addc_u32 s25, s39, s25
	s_and_b64 s[30:31], s[4:5], exec
	s_cselect_b32 s19, s25, s29
	s_cselect_b32 s51, s24, s28
	s_add_u32 s26, s26, 0x80080
	s_addc_u32 s27, s27, 0
	s_add_u32 s52, s28, 0x100
	v_mov_b32_e32 v2, 0
	s_addc_u32 s53, s29, 0
	s_mov_b32 s54, -2
	v_mov_b32_e32 v3, v2
	v_pk_mov_b32 v[4:5], v[2:3], v[2:3]
	v_pk_mov_b32 v[6:7], v[2:3], v[2:3]
	v_pk_mov_b32 v[8:9], v[2:3], v[2:3]
	v_pk_mov_b32 v[18:19], v[2:3], v[2:3]
	s_waitcnt vmcnt(0)
	v_pk_mov_b32 v[20:21], v[2:3], v[2:3]
	v_pk_mov_b32 v[22:23], v[2:3], v[2:3]
	v_pk_mov_b32 v[24:25], v[2:3], v[2:3]
	v_pk_mov_b32 v[34:35], v[2:3], v[2:3]
	v_pk_mov_b32 v[36:37], v[2:3], v[2:3]
	v_pk_mov_b32 v[38:39], v[2:3], v[2:3]
	v_pk_mov_b32 v[40:41], v[2:3], v[2:3]
	v_pk_mov_b32 v[50:51], v[2:3], v[2:3]
	v_pk_mov_b32 v[52:53], v[2:3], v[2:3]
	v_pk_mov_b32 v[54:55], v[2:3], v[2:3]
	v_pk_mov_b32 v[56:57], v[2:3], v[2:3]
	v_pk_mov_b32 v[10:11], v[2:3], v[2:3]
	v_pk_mov_b32 v[12:13], v[2:3], v[2:3]
	v_pk_mov_b32 v[14:15], v[2:3], v[2:3]
	v_pk_mov_b32 v[16:17], v[2:3], v[2:3]
	v_pk_mov_b32 v[26:27], v[2:3], v[2:3]
	v_pk_mov_b32 v[28:29], v[2:3], v[2:3]
	v_pk_mov_b32 v[30:31], v[2:3], v[2:3]
	v_pk_mov_b32 v[32:33], v[2:3], v[2:3]
	v_pk_mov_b32 v[42:43], v[2:3], v[2:3]
	v_pk_mov_b32 v[44:45], v[2:3], v[2:3]
	v_pk_mov_b32 v[46:47], v[2:3], v[2:3]
	v_pk_mov_b32 v[48:49], v[2:3], v[2:3]
	v_pk_mov_b32 v[58:59], v[2:3], v[2:3]
	v_pk_mov_b32 v[60:61], v[2:3], v[2:3]
	v_pk_mov_b32 v[62:63], v[2:3], v[2:3]
	v_pk_mov_b32 v[64:65], v[2:3], v[2:3]
	v_pk_mov_b32 v[66:67], v[2:3], v[2:3]
	v_pk_mov_b32 v[68:69], v[2:3], v[2:3]
	v_pk_mov_b32 v[70:71], v[2:3], v[2:3]
	v_pk_mov_b32 v[72:73], v[2:3], v[2:3]
	v_pk_mov_b32 v[82:83], v[2:3], v[2:3]
	v_pk_mov_b32 v[84:85], v[2:3], v[2:3]
	v_pk_mov_b32 v[86:87], v[2:3], v[2:3]
	v_pk_mov_b32 v[88:89], v[2:3], v[2:3]
	v_pk_mov_b32 v[98:99], v[2:3], v[2:3]
	v_pk_mov_b32 v[100:101], v[2:3], v[2:3]
	v_pk_mov_b32 v[102:103], v[2:3], v[2:3]
	v_pk_mov_b32 v[104:105], v[2:3], v[2:3]
	v_pk_mov_b32 v[114:115], v[2:3], v[2:3]
	v_pk_mov_b32 v[116:117], v[2:3], v[2:3]
	v_pk_mov_b32 v[118:119], v[2:3], v[2:3]
	v_pk_mov_b32 v[120:121], v[2:3], v[2:3]
	v_pk_mov_b32 v[74:75], v[2:3], v[2:3]
	v_pk_mov_b32 v[76:77], v[2:3], v[2:3]
	v_pk_mov_b32 v[78:79], v[2:3], v[2:3]
	v_pk_mov_b32 v[80:81], v[2:3], v[2:3]
	v_pk_mov_b32 v[90:91], v[2:3], v[2:3]
	v_pk_mov_b32 v[92:93], v[2:3], v[2:3]
	v_pk_mov_b32 v[94:95], v[2:3], v[2:3]
	v_pk_mov_b32 v[96:97], v[2:3], v[2:3]
	v_pk_mov_b32 v[106:107], v[2:3], v[2:3]
	v_pk_mov_b32 v[108:109], v[2:3], v[2:3]
	v_pk_mov_b32 v[110:111], v[2:3], v[2:3]
	v_pk_mov_b32 v[112:113], v[2:3], v[2:3]
	v_pk_mov_b32 v[122:123], v[2:3], v[2:3]
	v_pk_mov_b32 v[124:125], v[2:3], v[2:3]
	v_pk_mov_b32 v[126:127], v[2:3], v[2:3]
	v_pk_mov_b32 v[128:129], v[2:3], v[2:3]

; template <class Epi, class Sched, bool ALIGN_EPI = false, bool SP2 = false>
; __device__ __forceinline__ void gemm_phase(PG8_LAS unsigned char* lds, const Gemm g, const Sched& S, const Epi& E, int wave_in) {
;     ...
;         const char* nA = has_next ? (const char*)g.A + (size_t)nxt.pm * tstepA : cA; const char* nB = has_next ? (const char*)g.Bt + (size_t)nxt.pn * tstep : cB;
;     ...
; #pragma unroll
;         for (int a = 0; a < 2; ++a)
; #pragma unroll
;             for (int b = 0; b < 2; ++b)
; #pragma unroll
;                 for (int m = 0; m < 4; ++m)
; #pragma unroll
;                     for (int n = 0; n < 2; ++n) acc[a][b][m][n] = (f32x4){0.f, 0.f, 0.f, 0.f};
;         cur = nxt; cA = nA; cB = nB; ++ui;
.LBB0_127:
	s_ashr_i32 s17, s16, 31
	s_lshl_b64 s[18:19], s[16:17], 18
	s_add_u32 s18, s14, s18
	s_addc_u32 s19, s15, s19
	s_and_b64 s[20:21], s[0:1], exec
	s_cselect_b32 s17, s19, s23
	s_cselect_b32 s42, s18, s22
	s_ashr_i32 s11, s10, 31
	s_lshl_b64 s[20:21], s[10:11], 18
	s_add_u32 s20, s28, s20
	s_addc_u32 s21, s29, s21
	s_and_b64 s[26:27], s[0:1], exec
	s_cselect_b32 s11, s21, s25
	s_cselect_b32 s43, s20, s24
	s_add_u32 s22, s22, 0x20080
	s_addc_u32 s23, s23, 0
	s_add_u32 s44, s24, 0x100
	v_mov_b32_e32 v2, 0
	s_addc_u32 s45, s25, 0
	s_mov_b32 s46, -2
	v_mov_b32_e32 v3, v2
	v_pk_mov_b32 v[4:5], v[2:3], v[2:3]
	v_pk_mov_b32 v[6:7], v[2:3], v[2:3]
	v_pk_mov_b32 v[8:9], v[2:3], v[2:3]
	v_pk_mov_b32 v[18:19], v[2:3], v[2:3]
	s_waitcnt vmcnt(0)
	v_pk_mov_b32 v[20:21], v[2:3], v[2:3]
	v_pk_mov_b32 v[22:23], v[2:3], v[2:3]
	v_pk_mov_b32 v[24:25], v[2:3], v[2:3]
	v_pk_mov_b32 v[34:35], v[2:3], v[2:3]
	v_pk_mov_b32 v[36:37], v[2:3], v[2:3]
	v_pk_mov_b32 v[38:39], v[2:3], v[2:3]
	v_pk_mov_b32 v[40:41], v[2:3], v[2:3]
	v_pk_mov_b32 v[50:51], v[2:3], v[2:3]
	v_pk_mov_b32 v[52:53], v[2:3], v[2:3]
	v_pk_mov_b32 v[54:55], v[2:3], v[2:3]
	v_pk_mov_b32 v[56:57], v[2:3], v[2:3]
	v_pk_mov_b32 v[10:11], v[2:3], v[2:3]
	v_pk_mov_b32 v[12:13], v[2:3], v[2:3]
	v_pk_mov_b32 v[14:15], v[2:3], v[2:3]
	v_pk_mov_b32 v[16:17], v[2:3], v[2:3]
	v_pk_mov_b32 v[26:27], v[2:3], v[2:3]
	v_pk_mov_b32 v[28:29], v[2:3], v[2:3]
	v_pk_mov_b32 v[30:31], v[2:3], v[2:3]
	v_pk_mov_b32 v[32:33], v[2:3], v[2:3]
	v_pk_mov_b32 v[42:43], v[2:3], v[2:3]
	v_pk_mov_b32 v[44:45], v[2:3], v[2:3]
	v_pk_mov_b32 v[46:47], v[2:3], v[2:3]
	v_pk_mov_b32 v[48:49], v[2:3], v[2:3]
	v_pk_mov_b32 v[74:75], v[2:3], v[2:3]
	v_pk_mov_b32 v[76:77], v[2:3], v[2:3]
	v_pk_mov_b32 v[78:79], v[2:3], v[2:3]
	v_pk_mov_b32 v[80:81], v[2:3], v[2:3]
	v_pk_mov_b32 v[82:83], v[2:3], v[2:3]
	v_pk_mov_b32 v[84:85], v[2:3], v[2:3]
	v_pk_mov_b32 v[86:87], v[2:3], v[2:3]
	v_pk_mov_b32 v[88:89], v[2:3], v[2:3]
	v_pk_mov_b32 v[98:99], v[2:3], v[2:3]
	v_pk_mov_b32 v[100:101], v[2:3], v[2:3]
	v_pk_mov_b32 v[102:103], v[2:3], v[2:3]
	v_pk_mov_b32 v[104:105], v[2:3], v[2:3]
	v_pk_mov_b32 v[114:115], v[2:3], v[2:3]
	v_pk_mov_b32 v[116:117], v[2:3], v[2:3]
	v_pk_mov_b32 v[118:119], v[2:3], v[2:3]
	v_pk_mov_b32 v[120:121], v[2:3], v[2:3]
	v_pk_mov_b32 v[130:131], v[2:3], v[2:3]
	v_pk_mov_b32 v[132:133], v[2:3], v[2:3]
	v_pk_mov_b32 v[134:135], v[2:3], v[2:3]
	v_pk_mov_b32 v[136:137], v[2:3], v[2:3]
	v_pk_mov_b32 v[90:91], v[2:3], v[2:3]
	v_pk_mov_b32 v[92:93], v[2:3], v[2:3]
	v_pk_mov_b32 v[94:95], v[2:3], v[2:3]
	v_pk_mov_b32 v[96:97], v[2:3], v[2:3]
	v_pk_mov_b32 v[106:107], v[2:3], v[2:3]
	v_pk_mov_b32 v[108:109], v[2:3], v[2:3]
	v_pk_mov_b32 v[110:111], v[2:3], v[2:3]
	v_pk_mov_b32 v[112:113], v[2:3], v[2:3]
	v_pk_mov_b32 v[122:123], v[2:3], v[2:3]
	v_pk_mov_b32 v[124:125], v[2:3], v[2:3]
	v_pk_mov_b32 v[126:127], v[2:3], v[2:3]
	v_pk_mov_b32 v[128:129], v[2:3], v[2:3]
	v_pk_mov_b32 v[138:139], v[2:3], v[2:3]
	v_pk_mov_b32 v[140:141], v[2:3], v[2:3]
	v_pk_mov_b32 v[142:143], v[2:3], v[2:3]
	v_pk_mov_b32 v[144:145], v[2:3], v[2:3]

; template <class Epi, class Sched, bool ALIGN_EPI = false, bool SP2 = false>
; __device__ __forceinline__ void gemm_phase(PG8_LAS unsigned char* lds, const Gemm g, const Sched& S, const Epi& E, int wave_in) {
;     ...
;         const char* nA = has_next ? (const char*)g.A + (size_t)nxt.pm * tstepA : cA; const char* nB = has_next ? (const char*)g.Bt + (size_t)nxt.pn * tstep : cB;
;     ...
; #pragma unroll
;         for (int a = 0; a < 2; ++a)
; #pragma unroll
;             for (int b = 0; b < 2; ++b)
; #pragma unroll
;                 for (int m = 0; m < 4; ++m)
; #pragma unroll
;                     for (int n = 0; n < 2; ++n) acc[a][b][m][n] = (f32x4){0.f, 0.f, 0.f, 0.f};
;         cur = nxt; cA = nA; cB = nB; ++ui;
.LBB0_276:
	s_ashr_i32 s19, s18, 31
	s_lshl_b64 s[4:5], s[18:19], 20
	v_readlane_b32 s20, v253, 60
	v_readlane_b32 s21, v253, 61
	s_add_u32 s20, s20, s4
	s_load_dwordx2 s[22:23], s[82:83], 0xf8
	s_addc_u32 s21, s21, s5
	s_and_b64 s[4:5], s[6:7], exec
	s_cselect_b32 s19, s21, s1
	s_cselect_b32 s36, s20, s0
	s_ashr_i32 s17, s16, 31
	s_lshl_b64 s[4:5], s[16:17], 20
	s_waitcnt lgkmcnt(0)
	s_add_u32 s22, s22, s4
	s_addc_u32 s23, s23, s5
	s_and_b64 s[4:5], s[6:7], exec
	s_cselect_b32 s17, s23, s3
	s_cselect_b32 s37, s22, s2
	s_add_u32 s0, s0, 0x80080
	s_addc_u32 s1, s1, 0
	s_add_u32 s38, s2, 0x100
	v_mov_b32_e32 v2, 0
	s_addc_u32 s39, s3, 0
	s_mov_b32 s40, -2
	v_mov_b32_e32 v3, v2
	v_pk_mov_b32 v[4:5], v[2:3], v[2:3]
	v_pk_mov_b32 v[6:7], v[2:3], v[2:3]
	v_pk_mov_b32 v[8:9], v[2:3], v[2:3]
	v_pk_mov_b32 v[18:19], v[2:3], v[2:3]
	s_waitcnt vmcnt(0)
	v_pk_mov_b32 v[20:21], v[2:3], v[2:3]
	v_pk_mov_b32 v[22:23], v[2:3], v[2:3]
	v_pk_mov_b32 v[24:25], v[2:3], v[2:3]
	v_pk_mov_b32 v[50:51], v[2:3], v[2:3]
	v_pk_mov_b32 v[52:53], v[2:3], v[2:3]
	v_pk_mov_b32 v[54:55], v[2:3], v[2:3]
	v_pk_mov_b32 v[56:57], v[2:3], v[2:3]
	v_pk_mov_b32 v[66:67], v[2:3], v[2:3]
	v_pk_mov_b32 v[68:69], v[2:3], v[2:3]
	v_pk_mov_b32 v[70:71], v[2:3], v[2:3]
	v_pk_mov_b32 v[72:73], v[2:3], v[2:3]
	v_pk_mov_b32 v[10:11], v[2:3], v[2:3]
	v_pk_mov_b32 v[12:13], v[2:3], v[2:3]
	v_pk_mov_b32 v[14:15], v[2:3], v[2:3]
	v_pk_mov_b32 v[16:17], v[2:3], v[2:3]
	v_pk_mov_b32 v[34:35], v[2:3], v[2:3]
	v_pk_mov_b32 v[36:37], v[2:3], v[2:3]
	v_pk_mov_b32 v[38:39], v[2:3], v[2:3]
	v_pk_mov_b32 v[40:41], v[2:3], v[2:3]
	v_pk_mov_b32 v[58:59], v[2:3], v[2:3]
	v_pk_mov_b32 v[60:61], v[2:3], v[2:3]
	v_pk_mov_b32 v[62:63], v[2:3], v[2:3]
	v_pk_mov_b32 v[64:65], v[2:3], v[2:3]
	v_pk_mov_b32 v[74:75], v[2:3], v[2:3]
	v_pk_mov_b32 v[76:77], v[2:3], v[2:3]
	v_pk_mov_b32 v[78:79], v[2:3], v[2:3]
	v_pk_mov_b32 v[80:81], v[2:3], v[2:3]
	v_pk_mov_b32 v[82:83], v[2:3], v[2:3]
	v_pk_mov_b32 v[84:85], v[2:3], v[2:3]
	v_pk_mov_b32 v[86:87], v[2:3], v[2:3]
	v_pk_mov_b32 v[88:89], v[2:3], v[2:3]
	v_pk_mov_b32 v[98:99], v[2:3], v[2:3]
	v_pk_mov_b32 v[100:101], v[2:3], v[2:3]
	v_pk_mov_b32 v[102:103], v[2:3], v[2:3]
	v_pk_mov_b32 v[104:105], v[2:3], v[2:3]
	v_pk_mov_b32 v[114:115], v[2:3], v[2:3]
	v_pk_mov_b32 v[116:117], v[2:3], v[2:3]
	v_pk_mov_b32 v[118:119], v[2:3], v[2:3]
	v_pk_mov_b32 v[120:121], v[2:3], v[2:3]
	v_pk_mov_b32 v[130:131], v[2:3], v[2:3]
	v_pk_mov_b32 v[132:133], v[2:3], v[2:3]
	v_pk_mov_b32 v[134:135], v[2:3], v[2:3]
	v_pk_mov_b32 v[136:137], v[2:3], v[2:3]
	v_pk_mov_b32 v[90:91], v[2:3], v[2:3]
	v_pk_mov_b32 v[92:93], v[2:3], v[2:3]
	v_pk_mov_b32 v[94:95], v[2:3], v[2:3]
	v_pk_mov_b32 v[96:97], v[2:3], v[2:3]
	v_pk_mov_b32 v[106:107], v[2:3], v[2:3]
	v_pk_mov_b32 v[108:109], v[2:3], v[2:3]
	v_pk_mov_b32 v[110:111], v[2:3], v[2:3]
	v_pk_mov_b32 v[112:113], v[2:3], v[2:3]
	v_pk_mov_b32 v[122:123], v[2:3], v[2:3]
	v_pk_mov_b32 v[124:125], v[2:3], v[2:3]
	v_pk_mov_b32 v[126:127], v[2:3], v[2:3]
	v_pk_mov_b32 v[128:129], v[2:3], v[2:3]
	v_pk_mov_b32 v[138:139], v[2:3], v[2:3]
	v_pk_mov_b32 v[140:141], v[2:3], v[2:3]
	v_pk_mov_b32 v[142:143], v[2:3], v[2:3]
	v_pk_mov_b32 v[144:145], v[2:3], v[2:3]

; template <class Epi, class Sched, bool ALIGN_EPI = false, bool SP2 = false>
; __device__ __forceinline__ void gemm_phase(PG8_LAS unsigned char* lds, const Gemm g, const Sched& S, const Epi& E, int wave_in) {
;     ...
; #pragma unroll
;         for (int a = 0; a < 2; ++a)
; #pragma unroll
;             for (int b = 0; b < 2; ++b)
; #pragma unroll
;                 for (int m = 0; m < 4; ++m)
; #pragma unroll
;                     for (int n = 0; n < 2; ++n) acc[a][b][m][n] = (f32x4){0.f, 0.f, 0.f, 0.f};
;         cur = nxt; cA = nA; cB = nB; ++ui;
.LBB0_403:
	s_add_u32 s4, s24, 0x80
	s_addc_u32 s5, s25, 0
	s_add_u32 s24, s6, 0x100
	v_mov_b32_e32 v2, 0
	s_addc_u32 s25, s7, 0
	s_mov_b32 s6, 0
	v_mov_b32_e32 v3, v2
	v_pk_mov_b32 v[4:5], v[2:3], v[2:3]
	s_waitcnt lgkmcnt(0)
	v_pk_mov_b32 v[6:7], v[2:3], v[2:3]
	v_pk_mov_b32 v[8:9], v[2:3], v[2:3]
	v_pk_mov_b32 v[18:19], v[2:3], v[2:3]
	v_pk_mov_b32 v[20:21], v[2:3], v[2:3]
	v_pk_mov_b32 v[22:23], v[2:3], v[2:3]
	s_waitcnt vmcnt(0)
	v_pk_mov_b32 v[24:25], v[2:3], v[2:3]
	v_pk_mov_b32 v[34:35], v[2:3], v[2:3]
	v_pk_mov_b32 v[36:37], v[2:3], v[2:3]
	v_pk_mov_b32 v[38:39], v[2:3], v[2:3]
	v_pk_mov_b32 v[40:41], v[2:3], v[2:3]
	v_pk_mov_b32 v[50:51], v[2:3], v[2:3]
	v_pk_mov_b32 v[52:53], v[2:3], v[2:3]
	v_pk_mov_b32 v[54:55], v[2:3], v[2:3]
	v_pk_mov_b32 v[56:57], v[2:3], v[2:3]
	v_pk_mov_b32 v[10:11], v[2:3], v[2:3]
	v_pk_mov_b32 v[12:13], v[2:3], v[2:3]
	v_pk_mov_b32 v[14:15], v[2:3], v[2:3]
	v_pk_mov_b32 v[16:17], v[2:3], v[2:3]
	v_pk_mov_b32 v[26:27], v[2:3], v[2:3]
	v_pk_mov_b32 v[28:29], v[2:3], v[2:3]
	v_pk_mov_b32 v[30:31], v[2:3], v[2:3]
	v_pk_mov_b32 v[32:33], v[2:3], v[2:3]
	v_pk_mov_b32 v[42:43], v[2:3], v[2:3]
	v_pk_mov_b32 v[44:45], v[2:3], v[2:3]
	v_pk_mov_b32 v[46:47], v[2:3], v[2:3]
	v_pk_mov_b32 v[48:49], v[2:3], v[2:3]
	v_pk_mov_b32 v[58:59], v[2:3], v[2:3]
	v_pk_mov_b32 v[60:61], v[2:3], v[2:3]
	v_pk_mov_b32 v[62:63], v[2:3], v[2:3]
	v_pk_mov_b32 v[64:65], v[2:3], v[2:3]
	v_pk_mov_b32 v[66:67], v[2:3], v[2:3]
	v_pk_mov_b32 v[68:69], v[2:3], v[2:3]
	v_pk_mov_b32 v[70:71], v[2:3], v[2:3]
	v_pk_mov_b32 v[72:73], v[2:3], v[2:3]
	v_pk_mov_b32 v[82:83], v[2:3], v[2:3]
	v_pk_mov_b32 v[84:85], v[2:3], v[2:3]
	v_pk_mov_b32 v[86:87], v[2:3], v[2:3]
	v_pk_mov_b32 v[88:89], v[2:3], v[2:3]
	v_pk_mov_b32 v[98:99], v[2:3], v[2:3]
	v_pk_mov_b32 v[100:101], v[2:3], v[2:3]
	v_pk_mov_b32 v[102:103], v[2:3], v[2:3]
	v_pk_mov_b32 v[104:105], v[2:3], v[2:3]
	v_pk_mov_b32 v[114:115], v[2:3], v[2:3]
	v_pk_mov_b32 v[116:117], v[2:3], v[2:3]
	v_pk_mov_b32 v[118:119], v[2:3], v[2:3]
	v_pk_mov_b32 v[120:121], v[2:3], v[2:3]
	v_pk_mov_b32 v[74:75], v[2:3], v[2:3]
	v_pk_mov_b32 v[76:77], v[2:3], v[2:3]
	v_pk_mov_b32 v[78:79], v[2:3], v[2:3]
	v_pk_mov_b32 v[80:81], v[2:3], v[2:3]
	v_pk_mov_b32 v[90:91], v[2:3], v[2:3]
	v_pk_mov_b32 v[92:93], v[2:3], v[2:3]
	v_pk_mov_b32 v[94:95], v[2:3], v[2:3]
	v_pk_mov_b32 v[96:97], v[2:3], v[2:3]
	v_pk_mov_b32 v[106:107], v[2:3], v[2:3]
	v_pk_mov_b32 v[108:109], v[2:3], v[2:3]
	v_pk_mov_b32 v[110:111], v[2:3], v[2:3]
	v_pk_mov_b32 v[112:113], v[2:3], v[2:3]
	v_pk_mov_b32 v[122:123], v[2:3], v[2:3]
	v_pk_mov_b32 v[124:125], v[2:3], v[2:3]
	v_pk_mov_b32 v[126:127], v[2:3], v[2:3]
	v_pk_mov_b32 v[128:129], v[2:3], v[2:3]
